# last arriver of a quad/XCD barrier skips the poll round trip (its returning atomic already proves everyone arrived)
# baseline (speedup 1.0000x reference)
; __device__ __forceinline__ unsigned xb_ld(unsigned* p)              { return __hip_atomic_load(p, __ATOMIC_RELAXED, __HIP_MEMORY_SCOPE_AGENT); }
; __device__ __forceinline__ unsigned xb_add(unsigned* p, unsigned v) { return __hip_atomic_fetch_add(p, v, __ATOMIC_RELAXED, __HIP_MEMORY_SCOPE_AGENT); }
; #define XB_SPIN(cond, bar) do { unsigned _sp = 0; while (cond) { __builtin_amdgcn_s_sleep(1); \
;     if ((++_sp & 255u) == 0u) { if (xb_ld(&(bar)[XB_TMO])) break; if (_sp > XB_SPIN_CAP) { atomicAdd(&(bar)[XB_TMO], 1u); break; } } } } while (0)
; __device__ __forceinline__ void xcd_barrier(const XcdBarrier& b) {
;     ...
;         const unsigned old = xb_add(&bar[XB_XSUB(b.x)], 1u);
;         const unsigned gen = old / nloc;
;         if (old + 1u == (gen + 1u) * nloc) {
;             __builtin_amdgcn_fence(__ATOMIC_RELEASE, "agent");
;             asm volatile("s_waitcnt vmcnt(0)" ::: "memory");
;             const unsigned og = xb_add(&bar[XB_TOP], 1u);
;             const unsigned tg = og / nx;
;             if (og + 1u == (tg + 1u) * nx) xb_add(&bar[XB_TOPGEN], 1u);
;             else XB_SPIN(xb_ld(&bar[XB_TOPGEN]) == tg, bar);
;             __builtin_amdgcn_fence(__ATOMIC_ACQUIRE, "agent");
;             xb_add(&bar[XB_XGEN(b.x)], 1u);
;             asm volatile("s_waitcnt vmcnt(0)" ::: "memory");
;         } else {
;             XB_SPIN(xb_ld(&bar[XB_XGEN(b.x)]) == gen, bar);
;             __builtin_amdgcn_fence(__ATOMIC_ACQUIRE, "agent");
;             asm volatile("s_waitcnt vmcnt(0)" ::: "memory");
;         }
.Lxk_known_P2:
	s_cmp_eq_u32 s4, 1
	s_cbranch_scc0 .Lxg_P2
	v_readlane_b32 s10, v254, 30
	v_readlane_b32 s11, v254, 31
	s_and_b32 s12, s1, 15
	s_lshl_b32 s12, s12, 8
	s_add_u32 s6, s10, 0x300080
	s_addc_u32 s7, s11, 0
	s_add_u32 s6, s6, s12
	s_addc_u32 s7, s7, 0
	s_add_u32 s12, s10, 0x300008
	s_addc_u32 s13, s11, 0
	v_mov_b32_e32 v6, s12
	v_mov_b32_e32 v7, s13
	v_mov_b32_e32 v8, 1
	flat_atomic_add v[6:7], v8
	v_mov_b32_e32 v2, s6
	v_mov_b32_e32 v3, s7
	v_mov_b32_e32 v4, 1
	flat_atomic_add v4, v[2:3], v4 sc0
	s_mov_b32 s8, 0
	s_waitcnt vmcnt(0) lgkmcnt(0)
	v_add_u32_e32 v12, 1, v4
	v_and_b32_e32 v4, 0xffffffe0, v4
	v_add_u32_e32 v4, 32, v4
	v_cmp_eq_u32_e32 vcc, v12, v4
	s_cbranch_vccnz .Lxl_done_P2

; __device__ __forceinline__ unsigned xb_ld(unsigned* p)              { return __hip_atomic_load(p, __ATOMIC_RELAXED, __HIP_MEMORY_SCOPE_AGENT); }
; __device__ __forceinline__ unsigned xb_add(unsigned* p, unsigned v) { return __hip_atomic_fetch_add(p, v, __ATOMIC_RELAXED, __HIP_MEMORY_SCOPE_AGENT); }
; #define XB_SPIN(cond, bar) do { unsigned _sp = 0; while (cond) { __builtin_amdgcn_s_sleep(1); \
;     if ((++_sp & 255u) == 0u) { if (xb_ld(&(bar)[XB_TMO])) break; if (_sp > XB_SPIN_CAP) { atomicAdd(&(bar)[XB_TMO], 1u); break; } } } } while (0)
; __device__ __forceinline__ void xcd_barrier(const XcdBarrier& b) {
;     ...
;         const unsigned old = xb_add(&bar[XB_XSUB(b.x)], 1u);
;         const unsigned gen = old / nloc;
;         if (old + 1u == (gen + 1u) * nloc) {
;             __builtin_amdgcn_fence(__ATOMIC_RELEASE, "agent");
;             asm volatile("s_waitcnt vmcnt(0)" ::: "memory");
;             const unsigned og = xb_add(&bar[XB_TOP], 1u);
;             const unsigned tg = og / nx;
;             if (og + 1u == (tg + 1u) * nx) xb_add(&bar[XB_TOPGEN], 1u);
;             else XB_SPIN(xb_ld(&bar[XB_TOPGEN]) == tg, bar);
;             __builtin_amdgcn_fence(__ATOMIC_ACQUIRE, "agent");
;             xb_add(&bar[XB_XGEN(b.x)], 1u);
;             asm volatile("s_waitcnt vmcnt(0)" ::: "memory");
;         } else {
;             XB_SPIN(xb_ld(&bar[XB_XGEN(b.x)]) == gen, bar);
;             __builtin_amdgcn_fence(__ATOMIC_ACQUIRE, "agent");
;             asm volatile("s_waitcnt vmcnt(0)" ::: "memory");
;         }
.LBB0_785:
	v_readlane_b32 s4, v254, 16
	v_readlane_b32 s18, v254, 30
	v_readlane_b32 s19, v254, 31
	s_mov_b64 s[72:73], s[18:19]
	s_getreg_b32 s1, hwreg(HW_REG_XCC_ID, 0, 4)
	s_waitcnt vmcnt(0)
	v_readlane_b32 s5, v254, 17
	v_readlane_b32 s6, v254, 18
	v_readlane_b32 s7, v254, 19
	v_readlane_b32 s8, v254, 20
	v_readlane_b32 s9, v254, 21
	v_readlane_b32 s10, v254, 22
	v_readlane_b32 s11, v254, 23
	v_readlane_b32 s12, v254, 24
	v_readlane_b32 s13, v254, 25
	v_readlane_b32 s14, v254, 26
	v_readlane_b32 s15, v254, 27
	v_readlane_b32 s16, v254, 28
	v_readlane_b32 s17, v254, 29
	s_barrier
	s_mov_b64 s[42:43], exec
	v_readlane_b32 s4, v254, 32
	v_readlane_b32 s5, v254, 33
	s_and_b64 s[4:5], s[42:43], s[4:5]
	s_mov_b64 exec, s[4:5]
	s_cbranch_execz .LBB0_829
	s_waitcnt vmcnt(0) lgkmcnt(0)
	v_mov_b32_e32 v0, 0x20008
	ds_read_b32 v2, v0
	s_waitcnt lgkmcnt(0)
	v_readfirstlane_b32 s4, v2
	s_nop 3
	s_cmp_eq_u32 s4, 1
	s_cbranch_scc0 .Lxg_P3
	v_readlane_b32 s10, v254, 30
	v_readlane_b32 s11, v254, 31
	s_and_b32 s12, s33, 7
	s_lshr_b32 s13, s33, 3
	s_and_b32 s13, s13, 7
	s_lshl_b32 s12, s12, 3
	s_or_b32 s12, s12, s13
	s_and_b32 s13, s12, 15
	s_lshl_b32 s13, s13, 8
	s_lshr_b32 s12, s12, 4
	s_lshl_b32 s12, s12, 2
	s_add_u32 s12, s12, s13
	s_add_u32 s6, s10, 0x300010
	s_addc_u32 s7, s11, 0
	s_add_u32 s6, s6, s12
	s_addc_u32 s7, s7, 0
	v_mov_b32_e32 v2, s6
	v_mov_b32_e32 v3, s7
	v_mov_b32_e32 v4, 1
	flat_atomic_add v4, v[2:3], v4 sc0
	s_mov_b32 s8, 0
	s_waitcnt vmcnt(0) lgkmcnt(0)
	v_add_u32_e32 v12, 1, v4
	v_and_b32_e32 v4, 0xfffffffc, v4
	v_add_u32_e32 v4, 4, v4
	v_cmp_eq_u32_e32 vcc, v12, v4
	s_cbranch_vccnz .Lxl_done_P3

; __device__ __forceinline__ unsigned xb_ld(unsigned* p)              { return __hip_atomic_load(p, __ATOMIC_RELAXED, __HIP_MEMORY_SCOPE_AGENT); }
; __device__ __forceinline__ unsigned xb_add(unsigned* p, unsigned v) { return __hip_atomic_fetch_add(p, v, __ATOMIC_RELAXED, __HIP_MEMORY_SCOPE_AGENT); }
; #define XB_SPIN(cond, bar) do { unsigned _sp = 0; while (cond) { __builtin_amdgcn_s_sleep(1); \
;     if ((++_sp & 255u) == 0u) { if (xb_ld(&(bar)[XB_TMO])) break; if (_sp > XB_SPIN_CAP) { atomicAdd(&(bar)[XB_TMO], 1u); break; } } } } while (0)
; __device__ __forceinline__ void xcd_barrier(const XcdBarrier& b) {
;     ...
;         const unsigned old = xb_add(&bar[XB_XSUB(b.x)], 1u);
;         const unsigned gen = old / nloc;
;         if (old + 1u == (gen + 1u) * nloc) {
;             __builtin_amdgcn_fence(__ATOMIC_RELEASE, "agent");
;             asm volatile("s_waitcnt vmcnt(0)" ::: "memory");
;             const unsigned og = xb_add(&bar[XB_TOP], 1u);
;             const unsigned tg = og / nx;
;             if (og + 1u == (tg + 1u) * nx) xb_add(&bar[XB_TOPGEN], 1u);
;             else XB_SPIN(xb_ld(&bar[XB_TOPGEN]) == tg, bar);
;             __builtin_amdgcn_fence(__ATOMIC_ACQUIRE, "agent");
;             xb_add(&bar[XB_XGEN(b.x)], 1u);
;             asm volatile("s_waitcnt vmcnt(0)" ::: "memory");
;         } else {
;             XB_SPIN(xb_ld(&bar[XB_XGEN(b.x)]) == gen, bar);
;             __builtin_amdgcn_fence(__ATOMIC_ACQUIRE, "agent");
;             asm volatile("s_waitcnt vmcnt(0)" ::: "memory");
;         }
.LBB0_867:
	v_readlane_b32 s4, v254, 16
	v_readlane_b32 s18, v254, 30
	v_readlane_b32 s19, v254, 31
	s_mov_b64 s[72:73], s[18:19]
	s_getreg_b32 s1, hwreg(HW_REG_XCC_ID, 0, 4)
	s_waitcnt vmcnt(0)
	v_readlane_b32 s5, v254, 17
	v_readlane_b32 s6, v254, 18
	v_readlane_b32 s7, v254, 19
	v_readlane_b32 s8, v254, 20
	v_readlane_b32 s9, v254, 21
	v_readlane_b32 s10, v254, 22
	v_readlane_b32 s11, v254, 23
	v_readlane_b32 s12, v254, 24
	v_readlane_b32 s13, v254, 25
	v_readlane_b32 s14, v254, 26
	v_readlane_b32 s15, v254, 27
	v_readlane_b32 s16, v254, 28
	v_readlane_b32 s17, v254, 29
	s_barrier
	s_mov_b64 s[42:43], exec
	v_readlane_b32 s4, v254, 32
	v_readlane_b32 s5, v254, 33
	s_and_b64 s[4:5], s[42:43], s[4:5]
	s_mov_b64 exec, s[4:5]
	s_cbranch_execz .LBB0_911
	s_waitcnt vmcnt(0) lgkmcnt(0)
	v_mov_b32_e32 v0, 0x20008
	ds_read_b32 v2, v0
	s_waitcnt lgkmcnt(0)
	v_readfirstlane_b32 s4, v2
	s_nop 3
	s_cmp_eq_u32 s4, 1
	s_cbranch_scc0 .Lxg_P4
	v_readlane_b32 s10, v254, 30
	v_readlane_b32 s11, v254, 31
	s_and_b32 s12, s33, 7
	s_lshr_b32 s13, s33, 3
	s_and_b32 s13, s13, 7
	s_lshl_b32 s12, s12, 3
	s_or_b32 s12, s12, s13
	s_and_b32 s13, s12, 15
	s_lshl_b32 s13, s13, 8
	s_lshr_b32 s12, s12, 4
	s_lshl_b32 s12, s12, 2
	s_add_u32 s12, s12, s13
	s_add_u32 s6, s10, 0x300010
	s_addc_u32 s7, s11, 0
	s_add_u32 s6, s6, s12
	s_addc_u32 s7, s7, 0
	s_add_u32 s12, s10, 0x300008
	s_addc_u32 s13, s11, 0
	v_mov_b32_e32 v6, s12
	v_mov_b32_e32 v7, s13
	v_readlane_b32 s12, v253, 22
	s_nop 3
	s_lshl_b32 s12, s12, 2
	s_add_i32 s12, s12, s44
	s_add_i32 s12, s12, 1
	s_lshl_b32 s12, s12, 8
	v_mov_b32_e32 v9, s12
	v_mov_b32_e32 v2, s6
	v_mov_b32_e32 v3, s7
	v_mov_b32_e32 v4, 1
	flat_atomic_add v4, v[2:3], v4 sc0
	s_mov_b32 s8, 0
	s_waitcnt vmcnt(0) lgkmcnt(0)
	v_add_u32_e32 v12, 1, v4
	v_and_b32_e32 v4, 0xfffffffc, v4
	v_add_u32_e32 v4, 4, v4

; __device__ __forceinline__ unsigned xb_ld(unsigned* p)              { return __hip_atomic_load(p, __ATOMIC_RELAXED, __HIP_MEMORY_SCOPE_AGENT); }
; __device__ __forceinline__ unsigned xb_add(unsigned* p, unsigned v) { return __hip_atomic_fetch_add(p, v, __ATOMIC_RELAXED, __HIP_MEMORY_SCOPE_AGENT); }
; #define XB_SPIN(cond, bar) do { unsigned _sp = 0; while (cond) { __builtin_amdgcn_s_sleep(1); \
;     if ((++_sp & 255u) == 0u) { if (xb_ld(&(bar)[XB_TMO])) break; if (_sp > XB_SPIN_CAP) { atomicAdd(&(bar)[XB_TMO], 1u); break; } } } } while (0)
; __device__ __forceinline__ void xcd_barrier(const XcdBarrier& b) {
;     ...
;         const unsigned old = xb_add(&bar[XB_XSUB(b.x)], 1u);
;         const unsigned gen = old / nloc;
;         if (old + 1u == (gen + 1u) * nloc) {
;             __builtin_amdgcn_fence(__ATOMIC_RELEASE, "agent");
;             asm volatile("s_waitcnt vmcnt(0)" ::: "memory");
;             const unsigned og = xb_add(&bar[XB_TOP], 1u);
;             const unsigned tg = og / nx;
;             if (og + 1u == (tg + 1u) * nx) xb_add(&bar[XB_TOPGEN], 1u);
;             else XB_SPIN(xb_ld(&bar[XB_TOPGEN]) == tg, bar);
;             __builtin_amdgcn_fence(__ATOMIC_ACQUIRE, "agent");
;             xb_add(&bar[XB_XGEN(b.x)], 1u);
;             asm volatile("s_waitcnt vmcnt(0)" ::: "memory");
;         } else {
;             XB_SPIN(xb_ld(&bar[XB_XGEN(b.x)]) == gen, bar);
;             __builtin_amdgcn_fence(__ATOMIC_ACQUIRE, "agent");
;             asm volatile("s_waitcnt vmcnt(0)" ::: "memory");
;         }
.LBB0_931:
	v_readlane_b32 s4, v254, 16
	v_readlane_b32 s18, v254, 30
	v_readlane_b32 s19, v254, 31
	s_mov_b64 s[72:73], s[18:19]
	s_getreg_b32 s1, hwreg(HW_REG_XCC_ID, 0, 4)
	s_waitcnt vmcnt(0)
	v_readlane_b32 s5, v254, 17
	v_readlane_b32 s6, v254, 18
	v_readlane_b32 s7, v254, 19
	v_readlane_b32 s8, v254, 20
	v_readlane_b32 s9, v254, 21
	v_readlane_b32 s10, v254, 22
	v_readlane_b32 s11, v254, 23
	v_readlane_b32 s12, v254, 24
	v_readlane_b32 s13, v254, 25
	v_readlane_b32 s14, v254, 26
	v_readlane_b32 s15, v254, 27
	v_readlane_b32 s16, v254, 28
	v_readlane_b32 s17, v254, 29
	s_barrier
	s_mov_b64 s[4:5], exec
	v_readlane_b32 s6, v254, 32
	v_readlane_b32 s7, v254, 33
	s_and_b64 s[6:7], s[4:5], s[6:7]
	s_xor_b64 s[42:43], s[6:7], s[4:5]
	s_mov_b64 exec, s[6:7]
	s_cbranch_execz .LBB0_976
	s_waitcnt vmcnt(0) lgkmcnt(0)
	v_mov_b32_e32 v0, 0x20008
	ds_read_b32 v2, v0
	s_waitcnt lgkmcnt(0)
	v_readfirstlane_b32 s4, v2
	s_nop 3
	s_cmp_eq_u32 s4, 1
	s_cbranch_scc0 .Lxg_P5
	v_readlane_b32 s10, v254, 30
	v_readlane_b32 s11, v254, 31
	s_and_b32 s12, s33, 7
	s_lshr_b32 s13, s33, 3
	s_and_b32 s13, s13, 7
	s_lshl_b32 s12, s12, 3
	s_or_b32 s12, s12, s13
	s_and_b32 s13, s12, 15
	s_lshl_b32 s13, s13, 8
	s_lshr_b32 s12, s12, 4
	s_lshl_b32 s12, s12, 2
	s_add_u32 s12, s12, s13
	s_add_u32 s6, s10, 0x300010
	s_addc_u32 s7, s11, 0
	s_add_u32 s6, s6, s12
	s_addc_u32 s7, s7, 0
	v_mov_b32_e32 v2, s6
	v_mov_b32_e32 v3, s7
	v_mov_b32_e32 v4, 1
	flat_atomic_add v4, v[2:3], v4 sc0
	s_mov_b32 s8, 0
	s_waitcnt vmcnt(0) lgkmcnt(0)
	v_add_u32_e32 v12, 1, v4
	v_and_b32_e32 v4, 0xfffffffc, v4
	v_add_u32_e32 v4, 4, v4
	v_cmp_eq_u32_e32 vcc, v12, v4
	s_cbranch_vccnz .Lxl_done_P5

; __device__ __forceinline__ unsigned xb_ld(unsigned* p)              { return __hip_atomic_load(p, __ATOMIC_RELAXED, __HIP_MEMORY_SCOPE_AGENT); }
; __device__ __forceinline__ unsigned xb_add(unsigned* p, unsigned v) { return __hip_atomic_fetch_add(p, v, __ATOMIC_RELAXED, __HIP_MEMORY_SCOPE_AGENT); }
; #define XB_SPIN(cond, bar) do { unsigned _sp = 0; while (cond) { __builtin_amdgcn_s_sleep(1); \
;     if ((++_sp & 255u) == 0u) { if (xb_ld(&(bar)[XB_TMO])) break; if (_sp > XB_SPIN_CAP) { atomicAdd(&(bar)[XB_TMO], 1u); break; } } } } while (0)
; __device__ __forceinline__ void xcd_barrier(const XcdBarrier& b) {
;     ...
;         const unsigned old = xb_add(&bar[XB_XSUB(b.x)], 1u);
;         const unsigned gen = old / nloc;
;         if (old + 1u == (gen + 1u) * nloc) {
;             __builtin_amdgcn_fence(__ATOMIC_RELEASE, "agent");
;             asm volatile("s_waitcnt vmcnt(0)" ::: "memory");
;             const unsigned og = xb_add(&bar[XB_TOP], 1u);
;             const unsigned tg = og / nx;
;             if (og + 1u == (tg + 1u) * nx) xb_add(&bar[XB_TOPGEN], 1u);
;             else XB_SPIN(xb_ld(&bar[XB_TOPGEN]) == tg, bar);
;             __builtin_amdgcn_fence(__ATOMIC_ACQUIRE, "agent");
;             xb_add(&bar[XB_XGEN(b.x)], 1u);
;             asm volatile("s_waitcnt vmcnt(0)" ::: "memory");
;         } else {
;             XB_SPIN(xb_ld(&bar[XB_XGEN(b.x)]) == gen, bar);
;             __builtin_amdgcn_fence(__ATOMIC_ACQUIRE, "agent");
;             asm volatile("s_waitcnt vmcnt(0)" ::: "memory");
;         }
.LBB0_1014:
	v_readlane_b32 s0, v254, 16
	v_readlane_b32 s14, v254, 30
	v_readlane_b32 s15, v254, 31
	s_mov_b64 s[42:43], s[14:15]
	s_getreg_b32 s0, hwreg(HW_REG_XCC_ID, 0, 4)
	s_waitcnt vmcnt(0)
	v_readlane_b32 s1, v254, 17
	v_readlane_b32 s2, v254, 18
	v_readlane_b32 s3, v254, 19
	v_readlane_b32 s4, v254, 20
	v_readlane_b32 s5, v254, 21
	v_readlane_b32 s6, v254, 22
	v_readlane_b32 s7, v254, 23
	v_readlane_b32 s8, v254, 24
	v_readlane_b32 s9, v254, 25
	v_readlane_b32 s10, v254, 26
	v_readlane_b32 s11, v254, 27
	v_readlane_b32 s12, v254, 28
	v_readlane_b32 s13, v254, 29
	s_barrier
	s_mov_b64 s[34:35], exec
	v_readlane_b32 s2, v254, 32
	v_readlane_b32 s3, v254, 33
	s_and_b64 s[2:3], s[34:35], s[2:3]
	s_mov_b64 exec, s[2:3]
	s_cbranch_execz .LBB0_183
	s_waitcnt vmcnt(0) lgkmcnt(0)
	v_mov_b32_e32 v0, 0x20008
	ds_read_b32 v2, v0
	s_waitcnt lgkmcnt(0)
	v_readfirstlane_b32 s4, v2
	s_nop 3
	s_cmp_eq_u32 s44, 3
	s_cbranch_scc1 .Lxg_P6
	s_cmp_eq_u32 s4, 1
	s_cbranch_scc0 .Lxg_P6
	v_readlane_b32 s10, v254, 30
	v_readlane_b32 s11, v254, 31
	s_and_b32 s12, s33, 7
	s_lshr_b32 s13, s33, 3
	s_and_b32 s13, s13, 7
	s_lshl_b32 s12, s12, 3
	s_or_b32 s12, s12, s13
	s_and_b32 s13, s12, 15
	s_lshl_b32 s13, s13, 8
	s_lshr_b32 s12, s12, 4
	s_lshl_b32 s12, s12, 2
	s_add_u32 s12, s12, s13
	s_add_u32 s6, s10, 0x300010
	s_addc_u32 s7, s11, 0
	s_add_u32 s6, s6, s12
	s_addc_u32 s7, s7, 0
	s_add_u32 s12, s10, 0x30000c
	s_addc_u32 s13, s11, 0
	v_mov_b32_e32 v6, s12
	v_mov_b32_e32 v7, s13
	v_mov_b32_e32 v8, 1
	flat_atomic_add v[6:7], v8
	v_mov_b32_e32 v2, s6
	v_mov_b32_e32 v3, s7
	v_mov_b32_e32 v4, 1
	flat_atomic_add v4, v[2:3], v4 sc0
	s_mov_b32 s8, 0
	s_waitcnt vmcnt(0) lgkmcnt(0)
	v_add_u32_e32 v12, 1, v4
	v_and_b32_e32 v4, 0xfffffffc, v4
	v_add_u32_e32 v4, 4, v4
	v_cmp_eq_u32_e32 vcc, v12, v4
	s_cbranch_vccnz .Lxl_done_P6
